# latent rwkv runner chain wave, first chunk of the unrolled pair: LDS operands requested ahead and read straight into the MFMA operand tuples (three exposed LDS round trips and 14 moves removed from th
# speedup vs baseline: 1.0050x; 1.0042x over previous
.LBB0_2999:
	v_add_u32_e32 v53, s22, v51
	v_add_u32_e32 v2, 0xe000, v53
	ds_read2_b64 v[22:25], v2 offset1:4
	ds_read2_b64 v[26:29], v2 offset0:8 offset1:12
	v_add_u32_e32 v52, s22, v48
	v_add_u32_e32 v54, s22, v50
	ds_read_b64 v[30:31], v54 offset:57344
	ds_read_b64 v[32:33], v54 offset:57344
	ds_read_b64 v[2:3], v52 offset:62464
	v_cvt_pk_bf16_f32 v56, v18, v19
	v_cvt_pk_bf16_f32 v57, v20, v21
	v_cvt_pk_bf16_f32 v58, v14, v15
	v_cvt_pk_bf16_f32 v59, v16, v17
	v_mov_b32_e32 v5, v4
	ds_read_b64 v[66:67], v54 offset:57344
	s_waitcnt lgkmcnt(5)
	v_mfma_f32_16x16x32_bf16 v[22:25], v[22:25], v[56:59], 0
	v_cvt_pk_bf16_f32 v60, v10, v11
	v_cvt_pk_bf16_f32 v61, v12, v13
	v_cvt_pk_bf16_f32 v62, v6, v7
	v_cvt_pk_bf16_f32 v63, v8, v9
	v_add_u32_e32 v136, 0xe800, v52
	v_add_u32_e32 v137, 0xe000, v52
	ds_read_b64 v[124:125], v137
	ds_read_b64 v[126:127], v136 offset:512
	s_waitcnt lgkmcnt(6)
	v_mfma_f32_16x16x32_bf16 v[22:25], v[26:29], v[60:63], v[22:25]
	ds_read_b64 v[128:129], v137 offset:640
	ds_read_b64 v[130:131], v136 offset:1152
	s_waitcnt lgkmcnt(5)
	v_mfma_f32_16x16x32_bf16 v[22:25], v[2:5], v[30:33], v[22:25]
	v_add_u32_e32 v138, 0xec00, v52
	ds_read_b64 v[100:101], v137 offset:1280
	ds_read_b64 v[96:97], v137 offset:1920
	ds_read_b64 v[102:103], v138 offset:768
	ds_read_b64 v[98:99], v138 offset:1408
	v_add_u32_e32 v139, 0xe800, v53
	ds_read2_b64 v[108:111], v139 offset0:32 offset1:36
	ds_read2_b64 v[112:115], v139 offset0:40 offset1:44
	s_mov_b32 s25, 3
	s_nop 0
	v_cvt_pk_bf16_f32 v64, v22, v23
	v_cvt_pk_bf16_f32 v65, v24, v25
	v_add_u32_e32 v2, s22, v49
	v_add_u32_e32 v3, 0xe000, v2
	ds_read2_b64 v[116:119], v3 offset1:4
	v_add_u32_e32 v55, s22, v47
	s_waitcnt lgkmcnt(9)
	v_mfma_f32_16x16x32_bf16 v[22:25], v[124:127], v[64:67], v[18:21]
	s_andn2_b64 vcc, exec, s[8:9]
	s_waitcnt lgkmcnt(7)
	v_mfma_f32_16x16x32_bf16 v[14:17], v[128:131], v[64:67], v[14:17]
	s_mov_b32 s26, 3
	s_mov_b32 s28, 0
	s_waitcnt lgkmcnt(3)
	v_mfma_f32_16x16x32_bf16 v[18:21], v[96:99], v[64:67], v[6:9]
	v_mfma_f32_16x16x32_bf16 v[10:13], v[100:103], v[64:67], v[10:13]
	s_mov_b32 s27, s23
	ds_read_b128 v[38:41], v55 offset:57344
	ds_read_b128 v[34:37], v55 offset:57408
	ds_read_b128 v[30:33], v55 offset:57472
	ds_read_b128 v[26:29], v55 offset:57536
	s_waitcnt lgkmcnt(6)
	v_mfma_f32_16x16x32_bf16 v[132:135], v[108:111], v[56:59], 0
	s_waitcnt lgkmcnt(5)
	v_mfma_f32_16x16x32_bf16 v[6:9], v[112:115], v[60:63], v[132:135]
	s_waitcnt lgkmcnt(4)
	v_mfma_f32_16x16x32_bf16 v[6:9], v[116:119], v[64:67], v[6:9]
	s_cbranch_vccnz .LBB0_3001
	s_lshl_b32 s26, s21, 4
	s_add_i32 s26, s26, s20
	s_sub_i32 s27, 0x3f0, s26
	s_mov_b32 s28, 3
	s_mov_b32 s26, 0
